# attention P*V section: V^T operand reads double-buffered (two LDS reads in flight, counted lgkmcnt) instead of read-wait-MFMA per fragment
# baseline (speedup 1.0000x reference)
.LBB0_524:
	v_lshlrev_b32_e32 v18, 2, v32
	v_and_b32_e32 v34, 60, v18
	v_lshlrev_b32_e32 v190, 2, v34
	v_lshl_add_u64 v[16:17], v[16:17], 0, v[190:191]
	global_load_dwordx4 v[16:19], v[16:17], off
	v_add_u32_e32 v20, 0x200, v32
	v_ashrrev_i32_e32 v89, 4, v20
	v_lshl_add_u32 v229, v87, 11, v190
	v_lshl_add_u32 v244, v89, 11, v190
	s_and_b64 vcc, exec, s[12:13]
	v_add_u32_e32 v20, s3, v89
	s_cbranch_vccnz .LBB0_530
	v_min_i32_e32 v22, 0x40f, v20
	v_cmp_lt_i32_e32 vcc, s90, v20
	v_ashrrev_i32_e32 v23, 31, v22
	s_and_saveexec_b64 s[0:1], vcc
	s_xor_b64 s[0:1], exec, s[0:1]
	v_lshlrev_b64 v[20:21], 11, v[22:23]
	s_mov_b32 s4, 0xffe00000
	v_lshl_add_u64 v[20:21], s[36:37], 0, v[20:21]
	s_mov_b32 s5, -1
	v_lshl_add_u64 v[20:21], v[20:21], 0, s[4:5]
	s_andn2_saveexec_b64 s[0:1], s[0:1]
	v_lshlrev_b64 v[20:21], 11, v[22:23]
	v_lshl_add_u64 v[20:21], s[40:41], 0, v[20:21]
	s_or_b64 exec, exec, s[0:1]
	s_branch .LBB0_531

; __device__ __forceinline__ void item_attn(const Params& p, int l, int aidx) {
;     ...
;   ATT_LOAD_TILE(ntiles - 1, 0);
;   if (ntiles > 1) ATT_LOAD_TILE(ntiles - 2, 1);
.Lkvfast_p2:
	s_mov_b32 s2, s49
	s_ashr_i32 s3, s2, 31
	s_lshl_b64 s[100:101], s[2:3], 11
	s_add_u32 s100, s36, s100
	s_addc_u32 s101, s37, s101
	global_load_dwordx4 v[24:27], v229, s[100:101]
	global_load_dwordx4 v[28:31], v244, s[100:101]
	s_add_i32 s0, s48, s19
	s_addk_i32 s0, 0xff80
	s_ashr_i32 s1, s0, 31
	s_lshl_b64 s[2:3], s[0:1], 11
	s_add_u32 s4, s38, s2
	s_addc_u32 s5, s39, s3
	global_load_dword v109, v102, s[4:5]
	global_load_dword v111, v102, s[4:5] offset:2048
	s_add_u32 s4, s4, 0x1000
	s_addc_u32 s5, s5, 0
	global_load_dword v112, v102, s[4:5]
	global_load_dword v122, v102, s[4:5] offset:2048
	s_add_u32 s4, s4, 0x1000
	s_addc_u32 s5, s5, 0
	global_load_dword v123, v102, s[4:5]
	global_load_dword v124, v102, s[4:5] offset:2048
	s_add_u32 s4, s4, 0x1000
	s_addc_u32 s5, s5, 0
	global_load_dword v125, v102, s[4:5]
	global_load_dword v126, v102, s[4:5] offset:2048
	s_branch .Lkvp2_done

; __device__ __forceinline__ void item_attn(const Params& p, int l, int aidx) {
;     ...
;     if (kt > 1) ATT_LOAD_TILE(kt - 2, hs);
.Lkvfast_1:
	s_add_i32 s2, s49, 0xffffffc0
	s_ashr_i32 s3, s2, 31
	s_lshl_b64 s[100:101], s[2:3], 11
	s_add_u32 s100, s36, s100
	s_addc_u32 s101, s37, s101
	s_add_i32 s25, s48, s49
	global_load_dwordx4 v[16:19], v229, s[100:101]
	global_load_dwordx4 v[20:23], v244, s[100:101]
	s_add_i32 s2, s25, 0xffffffc0
	s_ashr_i32 s3, s2, 31
	s_lshl_b64 s[4:5], s[2:3], 11
	s_add_u32 s4, s38, s4
	s_addc_u32 s5, s39, s5
	global_load_dword v103, v102, s[4:5]
	global_load_dword v104, v102, s[4:5] offset:2048
	s_add_u32 s4, s4, 0x1000
	s_addc_u32 s5, s5, 0
	global_load_dword v105, v102, s[4:5]
	global_load_dword v106, v102, s[4:5] offset:2048
	s_add_u32 s4, s4, 0x1000
	s_addc_u32 s5, s5, 0
	global_load_dword v107, v102, s[4:5]
	global_load_dword v108, v102, s[4:5] offset:2048
	s_add_u32 s4, s4, 0x1000
	s_addc_u32 s5, s5, 0
	global_load_dword v110, v102, s[4:5]
	global_load_dword v113, v102, s[4:5] offset:2048
	s_add_u32 s4, s4, 0x800
	s_addc_u32 s5, s5, 0
	s_add_i32 s2, s25, 0xffffffc7
	s_ashr_i32 s3, s2, 31
	s_branch .LBB0_687

; __device__ __forceinline__ void item_attn(const Params& p, int l, int aidx) {
;     ...
; #pragma unroll
;       for (int kk = 0; kk < 2; ++kk) {
;         bf16x8 pb[2];
; #pragma unroll
;         for (int n = 0; n < 2; ++n) {
;           union { unsigned u[4]; bf16x8 v; } cv;
;           cv.u[0] = pk[2 * kk][n][0]; cv.u[1] = pk[2 * kk][n][1]; cv.u[2] = pk[2 * kk + 1][n][0]; cv.u[3] = pk[2 * kk + 1][n][1];
;           pb[n] = cv.v;
;         }
; #pragma unroll
;         for (int md = 0; md < 4; ++md) {
;           union { uint2 h[2]; bf16x8 v; } av;
;           av.h[0] = *reinterpret_cast<const uint2*>(VT + (md * 16 + fr) * 72 + kk * 32 + fq * 4);
;           av.h[1] = *reinterpret_cast<const uint2*>(VT + (md * 16 + fr) * 72 + kk * 32 + 16 + fq * 4);
; #pragma unroll
;           for (int n = 0; n < 2; ++n) oacc[md][n] = __builtin_amdgcn_mfma_f32_16x16x32_bf16(av.v, pb[n], oacc[md][n], 0, 0, 0);
;         }
;       }
;       wave_done = __all(((carry[0] < 1e-36f) || !rowv[0]) && ((carry[1] < 1e-36f) || !rowv[1]));
.LBB0_693:
	v_add_u32_e32 v90, v118, v119
	v_add_u32_e32 v91, 0x2000, v90
	v_add_u32_e32 v98, 0x2800, v90
	ds_read2_b64 v[94:97], v91 offset0:128 offset1:132
	ds_read2_b64 v[230:233], v98 offset0:160 offset1:164
	v_add_u32_e32 v99, 0x3000, v90
	v_add_u32_e32 v90, 0x3800, v90
	v_cmp_gt_f32_e32 vcc, s91, v93
	s_xor_b64 s[0:1], s[8:9], -1
	v_cmp_gt_f32_e64 s[20:21], s91, v92
	s_or_b64 s[2:3], s[10:11], s[20:21]
	s_or_b64 s[0:1], s[0:1], vcc
	s_waitcnt lgkmcnt(1)
	v_mfma_f32_16x16x32_bf16 v[60:63], v[94:97], v[68:71], v[60:63]
	s_and_b64 s[0:1], s[0:1], s[2:3]
	v_mfma_f32_16x16x32_bf16 v[44:47], v[94:97], v[72:75], v[44:47]
	ds_read2_b64 v[94:97], v99 offset0:192 offset1:196
	s_waitcnt lgkmcnt(1)
	v_mfma_f32_16x16x32_bf16 v[56:59], v[230:233], v[68:71], v[56:59]
	v_mfma_f32_16x16x32_bf16 v[36:39], v[230:233], v[72:75], v[36:39]
	ds_read2_b64 v[230:233], v90 offset0:224 offset1:228
	s_waitcnt lgkmcnt(1)
	v_mfma_f32_16x16x32_bf16 v[52:55], v[94:97], v[68:71], v[52:55]
	v_mfma_f32_16x16x32_bf16 v[40:43], v[94:97], v[72:75], v[40:43]
	ds_read2_b64 v[94:97], v91 offset0:136 offset1:140
	s_waitcnt lgkmcnt(1)
	v_mfma_f32_16x16x32_bf16 v[48:51], v[230:233], v[68:71], v[48:51]
	v_mfma_f32_16x16x32_bf16 v[32:35], v[230:233], v[72:75], v[32:35]
	ds_read2_b64 v[230:233], v98 offset0:168 offset1:172
	s_waitcnt lgkmcnt(1)
	v_mfma_f32_16x16x32_bf16 v[60:63], v[94:97], v[64:67], v[60:63]
	v_mfma_f32_16x16x32_bf16 v[44:47], v[94:97], v[76:79], v[44:47]
	ds_read2_b64 v[94:97], v99 offset0:200 offset1:204
	s_waitcnt lgkmcnt(1)
	v_mfma_f32_16x16x32_bf16 v[56:59], v[230:233], v[64:67], v[56:59]
	v_mfma_f32_16x16x32_bf16 v[36:39], v[230:233], v[76:79], v[36:39]
	ds_read2_b64 v[230:233], v90 offset0:232 offset1:236
	v_mov_b64_e32 v[90:91], v[92:93]
	s_waitcnt lgkmcnt(1)
	v_mfma_f32_16x16x32_bf16 v[52:55], v[94:97], v[64:67], v[52:55]
	v_mfma_f32_16x16x32_bf16 v[40:43], v[94:97], v[76:79], v[40:43]
	v_cndmask_b32_e64 v68, 0, 1, s[0:1]
	v_cmp_ne_u32_e32 vcc, 0, v68
	s_cmp_eq_u64 vcc, exec
	s_waitcnt lgkmcnt(0)
	v_mfma_f32_16x16x32_bf16 v[48:51], v[230:233], v[64:67], v[48:51]
	s_cselect_b64 s[0:1], -1, 0
	v_mfma_f32_16x16x32_bf16 v[32:35], v[230:233], v[76:79], v[32:35]

; __device__ __forceinline__ void item_attn(const Params& p, int l, int aidx) {
;     ...
;     if (kt > 1) ATT_LOAD_TILE(kt - 2, hs);
.Lkvfast_2:
	s_add_i32 s2, s49, 0xffffff80
	s_ashr_i32 s3, s2, 31
	s_lshl_b64 s[100:101], s[2:3], 11
	s_add_u32 s100, s36, s100
	s_addc_u32 s101, s37, s101
	s_add_i32 s26, s48, s49
	global_load_dwordx4 v[24:27], v229, s[100:101]
	global_load_dwordx4 v[28:31], v244, s[100:101]
	s_add_i32 s2, s26, 0xffffff80
	s_ashr_i32 s3, s2, 31
	s_lshl_b64 s[0:1], s[2:3], 11
	s_add_u32 s0, s38, s0
	s_addc_u32 s1, s39, s1
	global_load_dword v109, v102, s[0:1]
	global_load_dword v111, v102, s[0:1] offset:2048
	s_add_u32 s0, s0, 0x1000
	s_addc_u32 s1, s1, 0
	global_load_dword v112, v102, s[0:1]
	global_load_dword v122, v102, s[0:1] offset:2048
	s_add_u32 s0, s0, 0x1000
	s_addc_u32 s1, s1, 0
	global_load_dword v123, v102, s[0:1]
	global_load_dword v124, v102, s[0:1] offset:2048
	s_add_u32 s0, s0, 0x1000
	s_addc_u32 s1, s1, 0
	global_load_dword v125, v102, s[0:1]
	global_load_dword v126, v102, s[0:1] offset:2048
	s_add_u32 s0, s0, 0x800
	s_addc_u32 s1, s1, 0
	s_add_i32 s2, s26, 0xffffff87
	s_ashr_i32 s3, s2, 31
	s_branch .LBB0_760

; __device__ __forceinline__ void item_attn(const Params& p, int l, int aidx) {
;     ...
; #pragma unroll
;       for (int kk = 0; kk < 2; ++kk) {
;         bf16x8 pb[2];
; #pragma unroll
;         for (int n = 0; n < 2; ++n) {
;           union { unsigned u[4]; bf16x8 v; } cv;
;           cv.u[0] = pk[2 * kk][n][0]; cv.u[1] = pk[2 * kk][n][1]; cv.u[2] = pk[2 * kk + 1][n][0]; cv.u[3] = pk[2 * kk + 1][n][1];
;           pb[n] = cv.v;
;         }
; #pragma unroll
;         for (int md = 0; md < 4; ++md) {
;           union { uint2 h[2]; bf16x8 v; } av;
;           av.h[0] = *reinterpret_cast<const uint2*>(VT + (md * 16 + fr) * 72 + kk * 32 + fq * 4);
;           av.h[1] = *reinterpret_cast<const uint2*>(VT + (md * 16 + fr) * 72 + kk * 32 + 16 + fq * 4);
; #pragma unroll
;           for (int n = 0; n < 2; ++n) oacc[md][n] = __builtin_amdgcn_mfma_f32_16x16x32_bf16(av.v, pb[n], oacc[md][n], 0, 0, 0);
;         }
;       }
;       wave_done = __all(((carry[0] < 1e-36f) || !rowv[0]) && ((carry[1] < 1e-36f) || !rowv[1]));
.LBB0_766:
	v_add_u32_e32 v90, v118, v119
	v_add_u32_e32 v91, 0x2000, v90
	v_add_u32_e32 v98, 0x2800, v90
	ds_read2_b64 v[94:97], v91 offset0:128 offset1:132
	ds_read2_b64 v[230:233], v98 offset0:160 offset1:164
	v_add_u32_e32 v99, 0x3000, v90
	v_add_u32_e32 v90, 0x3800, v90
	v_cmp_gt_f32_e32 vcc, s91, v93
	s_xor_b64 s[0:1], s[8:9], -1
	v_cmp_gt_f32_e64 s[22:23], s91, v92
	s_or_b64 s[2:3], s[10:11], s[22:23]
	s_or_b64 s[0:1], s[0:1], vcc
	s_waitcnt lgkmcnt(1)
	v_mfma_f32_16x16x32_bf16 v[60:63], v[94:97], v[68:71], v[60:63]
	s_and_b64 s[0:1], s[0:1], s[2:3]
	v_mfma_f32_16x16x32_bf16 v[44:47], v[94:97], v[72:75], v[44:47]
	ds_read2_b64 v[94:97], v99 offset0:192 offset1:196
	s_waitcnt lgkmcnt(1)
	v_mfma_f32_16x16x32_bf16 v[56:59], v[230:233], v[68:71], v[56:59]
	v_mfma_f32_16x16x32_bf16 v[36:39], v[230:233], v[72:75], v[36:39]
	ds_read2_b64 v[230:233], v90 offset0:224 offset1:228
	s_waitcnt lgkmcnt(1)
	v_mfma_f32_16x16x32_bf16 v[52:55], v[94:97], v[68:71], v[52:55]
	v_mfma_f32_16x16x32_bf16 v[40:43], v[94:97], v[72:75], v[40:43]
	ds_read2_b64 v[94:97], v91 offset0:136 offset1:140
	s_waitcnt lgkmcnt(1)
	v_mfma_f32_16x16x32_bf16 v[48:51], v[230:233], v[68:71], v[48:51]
	v_mfma_f32_16x16x32_bf16 v[32:35], v[230:233], v[72:75], v[32:35]
	ds_read2_b64 v[230:233], v98 offset0:168 offset1:172
	s_waitcnt lgkmcnt(1)
	v_mfma_f32_16x16x32_bf16 v[60:63], v[94:97], v[64:67], v[60:63]
	v_mfma_f32_16x16x32_bf16 v[44:47], v[94:97], v[76:79], v[44:47]
	ds_read2_b64 v[94:97], v99 offset0:200 offset1:204
	s_waitcnt lgkmcnt(1)
	v_mfma_f32_16x16x32_bf16 v[56:59], v[230:233], v[64:67], v[56:59]
	v_mfma_f32_16x16x32_bf16 v[36:39], v[230:233], v[76:79], v[36:39]
	ds_read2_b64 v[230:233], v90 offset0:232 offset1:236
	v_mov_b64_e32 v[90:91], v[92:93]
	s_waitcnt lgkmcnt(1)
	v_mfma_f32_16x16x32_bf16 v[52:55], v[94:97], v[64:67], v[52:55]
	v_mfma_f32_16x16x32_bf16 v[40:43], v[94:97], v[76:79], v[40:43]
	v_cndmask_b32_e64 v68, 0, 1, s[0:1]
	v_cmp_ne_u32_e32 vcc, 0, v68
	s_cmp_eq_u64 vcc, exec
	s_waitcnt lgkmcnt(0)
	v_mfma_f32_16x16x32_bf16 v[48:51], v[230:233], v[64:67], v[48:51]
	s_cselect_b64 s[0:1], -1, 0
	v_mfma_f32_16x16x32_bf16 v[32:35], v[230:233], v[76:79], v[32:35]
